# attention items redistributed (3 per wave on WGs 0-63 which run an extra late-GEMM tile, 7 on the others) + pool GEMM zero-block skip
# baseline (speedup 1.0000x reference)
.LBB0_506:
	v_ashrrev_i32_e32 v0, 6, v198
	v_lshl_add_u32 v9, s82, 3, v0
	s_cmpk_lg_i32 s71, 0x100
	s_cbranch_scc1 .Lat_gen
	s_movk_i32 s98, 0x600
	s_movk_i32 s99, 0x29ff
	s_mov_b32 s0, 0xfffffe00
	s_cmp_lt_u32 s82, 64
	s_cselect_b32 s98, 0x200, s98
	s_cselect_b32 s99, 0x2fff, s99
	s_cselect_b32 s0, 0x2a00, s0
	v_add_u32_e32 v9, s0, v9
	s_branch .Lat_def
.Lat_gen:
	v_readlane_b32 s98, v252, 9
	s_movk_i32 s99, 0x2fff
.Lat_def:
	v_cmp_ge_i32_e32 vcc, s99, v9
	s_and_saveexec_b64 s[0:1], vcc
	s_cbranch_execz .LBB0_539
	v_lshlrev_b32_e32 v0, 1, v198
	v_and_b32_e32 v0, 24, v0
	v_and_b32_e32 v1, 3, v198
	s_movk_i32 s2, 0xffc0
	v_lshlrev_b32_e32 v194, 12, v199
	v_and_b32_e32 v2, 63, v198
	v_bfe_u32 v3, v198, 4, 2
	v_or3_b32 v118, v1, v0, s2
	s_waitcnt lgkmcnt(0)
	v_lshl_add_u64 v[0:1], s[38:39], 0, v[194:195]
	s_mov_b64 s[2:3], 0x2292b400
	v_lshlrev_b32_e32 v8, 3, v3
	v_lshl_add_u64 v[110:111], v[0:1], 0, s[2:3]
	v_lshlrev_b32_e32 v0, 2, v2
	v_lshlrev_b32_e32 v194, 1, v199
	s_add_u32 s34, s38, 0x299eb400
	v_or_b32_e32 v119, 0xffffffc0, v8
	v_xor_b32_e32 v120, 64, v0
	v_xor_b32_e32 v121, 0x80, v0
	v_lshl_add_u64 v[0:1], s[38:39], 0, v[194:195]
	s_mov_b64 s[2:3], 0x2412b400
	s_addc_u32 s35, s39, 0
	v_lshl_add_u64 v[112:113], v[0:1], 0, s[2:3]
	v_sub_u32_e32 v0, v119, v199
	s_add_u32 s42, s38, 0x2592b400
	v_and_b32_e32 v123, 48, v198
	v_add_u32_e32 v1, 64, v0
	s_movk_i32 s2, 0x81
	v_add_u32_e32 v0, 0xc0, v0
	s_addc_u32 s43, s39, 0
	v_lshlrev_b32_e32 v122, 2, v3
	v_or_b32_e32 v124, 4, v123
	v_or_b32_e32 v125, 8, v123
	v_or_b32_e32 v126, 12, v123
	v_cmp_gt_u32_e64 s[4:5], 16, v2
	v_cmp_gt_u32_e64 s[6:7], s2, v1
	s_movk_i32 s19, 0x81
	v_cmp_gt_u32_e64 s[8:9], s2, v0
	s_mov_b64 s[44:45], 0
	s_branch .LBB0_509
.LBB0_508:
	s_or_b64 exec, exec, s[2:3]
	v_add_u32_e32 v9, s98, v9
	v_cmp_lt_i32_e32 vcc, s99, v9
	s_or_b64 s[44:45], vcc, s[44:45]
	s_andn2_b64 exec, exec, s[44:45]
	s_cbranch_execz .LBB0_539
